# UP epilogue: the two 8-byte G stores per row merged into one 16-byte store (first half kept in spare registers)
# baseline (speedup 1.0000x reference)
.Lmy_u1_nodefer:
	v_mov_b32_e32 v170, v1
	v_mov_b32_e32 v171, v1
	v_mov_b32_e32 v106, v1
	v_mov_b32_dpp v170, v150 row_shr:1 row_mask:0xf bank_mask:0xf
	v_mov_b32_e32 v107, v1
	v_mov_b32_dpp v171, v151 row_shr:1 row_mask:0xf bank_mask:0xf
	v_mov_b32_dpp v106, v162 row_shr:1 row_mask:0xf bank_mask:0xf
	v_mov_b32_dpp v107, v163 row_shr:1 row_mask:0xf bank_mask:0xf
	v_pk_fma_f32 v[170:171], v[74:75], v[170:171], v[78:79]
	v_mov_b32_e32 v172, v1
	v_pk_fma_f32 v[170:171], v[98:99], v[106:107], v[170:171]
	v_mov_b32_e32 v173, v1
	v_pk_fma_f32 v[174:175], v[94:95], v[166:167], v[170:171]
	v_mov_b32_e32 v178, v1
	v_mul_f32_e32 v0, v174, v174
	v_fmamk_f32 v0, v0, 0xbdd2d3e2, v220
	v_mul_f32_e32 v0, v174, v0
	v_exp_f32_e32 v0, v0
	v_mov_b32_e32 v179, v1
	v_mov_b32_e32 v108, v1
	v_mov_b32_dpp v172, v152 row_shr:1 row_mask:0xf bank_mask:0xf
	v_add_f32_e32 v0, 1.0, v0
	v_rcp_f32_e32 v0, v0
	v_mov_b32_e32 v109, v1
	v_mov_b32_dpp v173, v153 row_shr:1 row_mask:0xf bank_mask:0xf
	v_mov_b32_e32 v170, v1
	v_mul_f32_e32 v0, v174, v0
	v_mul_f32_e32 v174, v175, v175
	v_fmamk_f32 v174, v174, 0xbdd2d3e2, v220
	v_mul_f32_e32 v174, v175, v174
	v_exp_f32_e32 v174, v174
	v_mov_b32_dpp v178, v146 row_shr:1 row_mask:0xf bank_mask:0xf
	v_mov_b32_e32 v171, v1
	v_mov_b32_dpp v179, v147 row_shr:1 row_mask:0xf bank_mask:0xf
	v_add_f32_e32 v174, 1.0, v174
	v_rcp_f32_e32 v174, v174
	v_mov_b32_dpp v108, v164 row_shr:1 row_mask:0xf bank_mask:0xf
	v_mov_b32_dpp v109, v165 row_shr:1 row_mask:0xf bank_mask:0xf
	v_pk_fma_f32 v[172:173], v[76:77], v[172:173], v[80:81]
	v_mov_b32_dpp v170, v158 row_shr:1 row_mask:0xf bank_mask:0xf
	v_mov_b32_dpp v171, v159 row_shr:1 row_mask:0xf bank_mask:0xf
	v_pk_fma_f32 v[178:179], v[86:87], v[178:179], v[90:91]
	v_pk_fma_f32 v[172:173], v[100:101], v[108:109], v[172:173]
	v_pk_fma_f32 v[178:179], v[82:83], v[170:171], v[178:179]
	v_pk_fma_f32 v[176:177], v[96:97], v[168:169], v[172:173]
	v_pk_fma_f32 v[178:179], v[70:71], v[154:155], v[178:179]
	v_mul_f32_e32 v174, v175, v174
	v_mul_f32_e32 v0, v0, v178
	v_mul_f32_e32 v174, v174, v179
	v_mul_f32_e32 v175, v177, v177
	v_cvt_pk_bf16_f32 v174, v0, v174
	v_mul_f32_e32 v0, v176, v176
	v_fmamk_f32 v175, v175, 0xbdd2d3e2, v220
	v_fmamk_f32 v0, v0, 0xbdd2d3e2, v220
	v_mul_f32_e32 v175, v177, v175
	v_mul_f32_e32 v0, v176, v0
	v_exp_f32_e32 v175, v175
	v_exp_f32_e32 v0, v0
	v_mov_b32_e32 v180, v1
	v_mov_b32_e32 v181, v1
	v_add_f32_e32 v175, 1.0, v175
	v_add_f32_e32 v0, 1.0, v0
	v_rcp_f32_e32 v175, v175
	v_mov_b32_e32 v172, v1
	v_mov_b32_dpp v180, v148 row_shr:1 row_mask:0xf bank_mask:0xf
	v_mov_b32_e32 v173, v1
	v_mov_b32_dpp v181, v149 row_shr:1 row_mask:0xf bank_mask:0xf
	v_rcp_f32_e32 v0, v0
	v_mov_b32_dpp v172, v160 row_shr:1 row_mask:0xf bank_mask:0xf
	v_mov_b32_dpp v173, v161 row_shr:1 row_mask:0xf bank_mask:0xf
	v_pk_fma_f32 v[180:181], v[88:89], v[180:181], v[92:93]
	v_mul_f32_e32 v175, v177, v175
	v_pk_fma_f32 v[180:181], v[84:85], v[172:173], v[180:181]
	v_mul_f32_e32 v0, v176, v0
	v_pk_fma_f32 v[180:181], v[72:73], v[156:157], v[180:181]
	s_nop 0
	v_mul_f32_e32 v175, v175, v181
	v_mul_f32_e32 v0, v0, v180
	v_cvt_pk_bf16_f32 v175, v0, v175
	s_and_saveexec_b64 s[30:31], s[4:5]
	s_cbranch_execz .LBB0_242
	s_movk_i32 s23, 0xc00
	v_mul_lo_u32 v0, v237, s23
	v_add_lshl_u32 v0, v0, v192, 1
	v_lshl_add_u64 v[176:177], s[8:9], 0, v[0:1]
	v_mov_b32_e32 v178, v174
	v_mov_b32_e32 v179, v175
.LBB0_242:
	s_or_b64 exec, exec, s[30:31]
	v_pk_fma_f32 v[106:107], v[74:75], v[106:107], v[78:79]
	v_pk_fma_f32 v[108:109], v[76:77], v[108:109], v[80:81]
	v_pk_fma_f32 v[106:107], v[98:99], v[166:167], v[106:107]
	v_pk_fma_f32 v[170:171], v[86:87], v[170:171], v[90:91]
	v_pk_fma_f32 v[106:107], v[94:95], v[142:143], v[106:107]
	v_pk_fma_f32 v[108:109], v[100:101], v[168:169], v[108:109]
	v_mul_f32_e32 v0, v106, v106
	v_fmamk_f32 v0, v0, 0xbdd2d3e2, v220
	v_mul_f32_e32 v0, v106, v0
	v_exp_f32_e32 v0, v0
	v_pk_fma_f32 v[170:171], v[82:83], v[154:155], v[170:171]
	v_pk_fma_f32 v[108:109], v[96:97], v[144:145], v[108:109]
	v_pk_fma_f32 v[170:171], v[70:71], v[138:139], v[170:171]
	v_add_f32_e32 v0, 1.0, v0
	v_rcp_f32_e32 v0, v0
	v_pk_fma_f32 v[172:173], v[88:89], v[172:173], v[92:93]
	v_mul_f32_e32 v0, v106, v0
	v_mul_f32_e32 v106, v107, v107
	v_fmamk_f32 v106, v106, 0xbdd2d3e2, v220
	v_mul_f32_e32 v106, v107, v106
	v_exp_f32_e32 v106, v106
	v_mul_f32_e32 v0, v0, v170
	v_pk_fma_f32 v[172:173], v[84:85], v[156:157], v[172:173]
	v_add_f32_e32 v106, 1.0, v106
	v_rcp_f32_e32 v106, v106
	v_pk_fma_f32 v[172:173], v[72:73], v[140:141], v[172:173]
	v_mul_f32_e32 v106, v107, v106
	v_mul_f32_e32 v106, v106, v171
	v_mul_f32_e32 v107, v109, v109
	v_cvt_pk_bf16_f32 v106, v0, v106
	v_mul_f32_e32 v0, v108, v108
	v_fmamk_f32 v107, v107, 0xbdd2d3e2, v220
	v_fmamk_f32 v0, v0, 0xbdd2d3e2, v220
	v_mul_f32_e32 v107, v109, v107
	v_mul_f32_e32 v0, v108, v0
	v_exp_f32_e32 v107, v107
	v_exp_f32_e32 v0, v0
	v_add_f32_e32 v107, 1.0, v107
	v_add_f32_e32 v0, 1.0, v0
	v_rcp_f32_e32 v107, v107
	v_rcp_f32_e32 v0, v0
	v_mul_f32_e32 v107, v109, v107
	v_mul_f32_e32 v0, v108, v0
	v_mul_f32_e32 v107, v107, v173
	v_mul_f32_e32 v0, v0, v172
	v_cvt_pk_bf16_f32 v107, v0, v107
	s_and_saveexec_b64 s[30:31], s[4:5]
	s_cbranch_execz .LBB0_244
	s_movk_i32 s23, 0xc00
	v_mul_lo_u32 v0, v240, s23
	v_add_lshl_u32 v0, v0, v192, 1
	v_lshl_add_u64 v[108:109], s[8:9], 0, v[0:1]
	v_mov_b32_e32 v180, v106
	v_mov_b32_e32 v181, v107
.LBB0_244:
	s_or_b64 exec, exec, s[30:31]
	v_pk_fma_f32 v[106:107], v[76:77], v[168:169], v[80:81]
	v_pk_fma_f32 v[108:109], v[74:75], v[166:167], v[78:79]
	v_pk_fma_f32 v[106:107], v[100:101], v[144:145], v[106:107]
	v_pk_fma_f32 v[144:145], v[76:77], v[144:145], v[80:81]
	v_pk_fma_f32 v[108:109], v[98:99], v[142:143], v[108:109]
	v_pk_fma_f32 v[106:107], v[96:97], v[152:153], v[106:107]
	v_pk_fma_f32 v[144:145], v[100:101], v[152:153], v[144:145]
	v_pk_fma_f32 v[152:153], v[86:87], v[154:155], v[90:91]
	v_pk_fma_f32 v[108:109], v[94:95], v[150:151], v[108:109]
	v_pk_fma_f32 v[152:153], v[82:83], v[138:139], v[152:153]
	v_pk_fma_f32 v[138:139], v[86:87], v[138:139], v[90:91]
	v_pk_fma_f32 v[152:153], v[70:71], v[146:147], v[152:153]
	v_pk_fma_f32 v[138:139], v[82:83], v[146:147], v[138:139]
	v_mul_f32_e32 v0, v108, v108
	v_mul_f32_e32 v146, v109, v109
	v_fmamk_f32 v0, v0, 0xbdd2d3e2, v220
	v_fmamk_f32 v146, v146, 0xbdd2d3e2, v220
	v_mul_f32_e32 v0, v108, v0
	v_mul_f32_e32 v146, v109, v146
	v_exp_f32_e32 v0, v0
	v_exp_f32_e32 v146, v146
	v_pk_fma_f32 v[142:143], v[74:75], v[142:143], v[78:79]
	s_movk_i32 s23, 0xc00
	v_add_f32_e32 v0, 1.0, v0
	v_add_f32_e32 v146, 1.0, v146
	v_rcp_f32_e32 v0, v0
	v_rcp_f32_e32 v146, v146
	v_pk_fma_f32 v[142:143], v[98:99], v[150:151], v[142:143]
	v_pk_fma_f32 v[150:151], v[88:89], v[156:157], v[92:93]
	v_mul_f32_e32 v0, v108, v0
	v_mul_f32_e32 v108, v109, v146
	v_mul_f32_e32 v109, v106, v106
	v_mul_f32_e32 v146, v107, v107
	v_fmamk_f32 v109, v109, 0xbdd2d3e2, v220
	v_fmamk_f32 v146, v146, 0xbdd2d3e2, v220
	v_mul_f32_e32 v109, v106, v109
	v_mul_f32_e32 v146, v107, v146
	v_exp_f32_e32 v109, v109
	v_exp_f32_e32 v146, v146
	v_pk_fma_f32 v[150:151], v[84:85], v[140:141], v[150:151]
	v_mul_f32_e32 v0, v152, v0
	v_add_f32_e32 v109, 1.0, v109
	v_add_f32_e32 v146, 1.0, v146
	v_rcp_f32_e32 v109, v109
	v_rcp_f32_e32 v146, v146
	v_mul_f32_e32 v108, v153, v108
	v_pk_fma_f32 v[150:151], v[72:73], v[148:149], v[150:151]
	v_cvt_pk_bf16_f32 v108, v0, v108
	v_mul_f32_e32 v0, v106, v109
	v_mul_f32_e32 v106, v107, v146
	v_mul_f32_e32 v106, v151, v106
	v_pk_fma_f32 v[142:143], v[94:95], v[162:163], v[142:143]
	v_mul_f32_e32 v0, v150, v0
	v_cvt_pk_bf16_f32 v109, v0, v106
	v_mad_u64_u32 v[106:107], s[30:31], v239, s23, v[192:193]
	v_mul_f32_e32 v107, v142, v142
	v_fmamk_f32 v107, v107, 0xbdd2d3e2, v220
	v_mul_f32_e32 v107, v142, v107
	v_exp_f32_e32 v107, v107
	v_mul_f32_e32 v146, v143, v143
	v_fmamk_f32 v146, v146, 0xbdd2d3e2, v220
	v_pk_fma_f32 v[140:141], v[88:89], v[140:141], v[92:93]
	v_add_f32_e32 v107, 1.0, v107
	v_rcp_f32_e32 v107, v107
	v_lshlrev_b32_e32 v0, 1, v106
	v_mul_f32_e32 v146, v143, v146
	v_pk_fma_f32 v[144:145], v[96:97], v[164:165], v[144:145]
	v_pk_fma_f32 v[140:141], v[84:85], v[148:149], v[140:141]
	v_pk_fma_f32 v[138:139], v[70:71], v[158:159], v[138:139]
	v_exp_f32_e32 v148, v146
	v_lshl_add_u64 v[146:147], s[8:9], 0, v[0:1]
	v_mul_f32_e32 v107, v142, v107
	v_mov_b32_e32 v194, v108
	v_mov_b32_e32 v195, v109
	v_mul_f32_e32 v107, v138, v107
	v_mul_f32_e32 v109, v144, v144
	v_mul_f32_e32 v138, v145, v145
	v_fmamk_f32 v109, v109, 0xbdd2d3e2, v220
	v_fmamk_f32 v138, v138, 0xbdd2d3e2, v220
	v_mul_f32_e32 v109, v144, v109
	v_mul_f32_e32 v138, v145, v138
	v_exp_f32_e32 v109, v109
	v_exp_f32_e32 v138, v138
	v_add_f32_e32 v148, 1.0, v148
	v_rcp_f32_e32 v148, v148
	v_add_f32_e32 v109, 1.0, v109
	v_add_f32_e32 v138, 1.0, v138
	v_rcp_f32_e32 v109, v109
	v_rcp_f32_e32 v138, v138
	v_mul_f32_e32 v108, v143, v148
	v_mul_f32_e32 v108, v139, v108
	v_pk_fma_f32 v[140:141], v[72:73], v[160:161], v[140:141]
	v_cvt_pk_bf16_f32 v108, v107, v108
	v_mul_f32_e32 v107, v144, v109
	v_mul_f32_e32 v109, v145, v138
	v_mul_f32_e32 v107, v140, v107
	v_mul_f32_e32 v109, v141, v109
	v_add_u32_e32 v146, 0xc00, v106
	v_cvt_pk_bf16_f32 v109, v107, v109
	v_lshlrev_b32_e32 v106, 1, v146
	v_mov_b32_e32 v107, v1
	v_lshl_add_u64 v[138:139], s[8:9], 0, v[106:107]
	v_mov_b32_e32 v140, v1
	v_mov_b32_e32 v141, v1
	v_mov_b32_e32 v196, v108
	v_mov_b32_e32 v197, v109
	v_mov_b32_e32 v108, v1
	v_mov_b32_dpp v140, v130 row_shr:1 row_mask:0xf bank_mask:0xf
	v_mov_b32_e32 v109, v1
	v_mov_b32_dpp v141, v131 row_shr:1 row_mask:0xf bank_mask:0xf
	v_mov_b32_dpp v108, v122 row_shr:1 row_mask:0xf bank_mask:0xf
	v_mov_b32_dpp v109, v123 row_shr:1 row_mask:0xf bank_mask:0xf
	v_pk_fma_f32 v[140:141], v[74:75], v[140:141], v[78:79]
	v_mov_b32_e32 v142, v1
	v_pk_fma_f32 v[140:141], v[98:99], v[108:109], v[140:141]
	v_mov_b32_e32 v143, v1
	v_pk_fma_f32 v[144:145], v[94:95], v[134:135], v[140:141]
	v_mov_b32_e32 v138, v1
	v_mul_f32_e32 v107, v144, v144
	v_mul_f32_e32 v147, v145, v145
	v_fmamk_f32 v107, v107, 0xbdd2d3e2, v220
	v_fmamk_f32 v147, v147, 0xbdd2d3e2, v220
	v_mul_f32_e32 v107, v144, v107
	v_mul_f32_e32 v147, v145, v147
	v_exp_f32_e32 v107, v107
	v_exp_f32_e32 v147, v147
	v_mov_b32_dpp v142, v132 row_shr:1 row_mask:0xf bank_mask:0xf
	v_mov_b32_e32 v139, v1
	v_add_f32_e32 v107, 1.0, v107
	v_add_f32_e32 v147, 1.0, v147
	v_mov_b32_dpp v143, v133 row_shr:1 row_mask:0xf bank_mask:0xf
	v_rcp_f32_e32 v107, v107
	v_rcp_f32_e32 v147, v147
	v_mov_b32_dpp v138, v124 row_shr:1 row_mask:0xf bank_mask:0xf
	v_mov_b32_dpp v139, v125 row_shr:1 row_mask:0xf bank_mask:0xf
	v_pk_fma_f32 v[142:143], v[76:77], v[142:143], v[80:81]
	v_mul_f32_e32 v107, v144, v107
	v_pk_fma_f32 v[142:143], v[100:101], v[138:139], v[142:143]
	v_mul_f32_e32 v144, v145, v147
	v_pk_fma_f32 v[148:149], v[96:97], v[136:137], v[142:143]
	v_mov_b32_e32 v150, v1
	v_mul_f32_e32 v145, v148, v148
	v_mul_f32_e32 v147, v149, v149
	v_fmamk_f32 v145, v145, 0xbdd2d3e2, v220
	v_fmamk_f32 v147, v147, 0xbdd2d3e2, v220
	v_mul_f32_e32 v145, v148, v145
	v_mul_f32_e32 v147, v149, v147
	v_exp_f32_e32 v145, v145
	v_exp_f32_e32 v147, v147
	v_mov_b32_e32 v151, v1
	v_mov_b32_e32 v140, v1
	v_mov_b32_dpp v150, v126 row_shr:1 row_mask:0xf bank_mask:0xf
	v_mov_b32_e32 v141, v1
	v_mov_b32_dpp v151, v127 row_shr:1 row_mask:0xf bank_mask:0xf
	v_add_f32_e32 v145, 1.0, v145
	v_add_f32_e32 v147, 1.0, v147
	v_mov_b32_dpp v140, v118 row_shr:1 row_mask:0xf bank_mask:0xf
	v_mov_b32_dpp v141, v119 row_shr:1 row_mask:0xf bank_mask:0xf
	v_mov_b32_e32 v152, v1
	v_mov_b32_e32 v153, v1
	v_pk_fma_f32 v[150:151], v[86:87], v[150:151], v[90:91]
	v_rcp_f32_e32 v145, v145
	v_rcp_f32_e32 v147, v147
	v_mov_b32_e32 v142, v1
	v_mov_b32_dpp v152, v128 row_shr:1 row_mask:0xf bank_mask:0xf
	v_mov_b32_e32 v143, v1
	v_mov_b32_dpp v153, v129 row_shr:1 row_mask:0xf bank_mask:0xf
	v_pk_fma_f32 v[150:151], v[82:83], v[140:141], v[150:151]
	v_mov_b32_dpp v142, v120 row_shr:1 row_mask:0xf bank_mask:0xf
	v_mov_b32_dpp v143, v121 row_shr:1 row_mask:0xf bank_mask:0xf
	v_pk_fma_f32 v[152:153], v[88:89], v[152:153], v[92:93]
	v_pk_fma_f32 v[150:151], v[70:71], v[114:115], v[150:151]
	v_pk_fma_f32 v[152:153], v[84:85], v[142:143], v[152:153]
	v_mul_f32_e32 v107, v107, v150
	v_mul_f32_e32 v144, v144, v151
	v_pk_fma_f32 v[152:153], v[72:73], v[116:117], v[152:153]
	v_cvt_pk_bf16_f32 v144, v107, v144
	v_mul_f32_e32 v107, v148, v145
	v_mul_f32_e32 v145, v149, v147
	v_mul_f32_e32 v145, v145, v153
	v_mul_f32_e32 v107, v107, v152
	v_cvt_pk_bf16_f32 v145, v107, v145
	s_and_saveexec_b64 s[30:31], s[4:5]
	s_cbranch_execz .LBB0_246
	v_mul_lo_u32 v107, v238, s23
	v_add_lshl_u32 v148, v107, v192, 1
	v_mov_b32_e32 v149, v1
	v_lshl_add_u64 v[148:149], s[8:9], 0, v[148:149]
	v_mov_b32_e32 v216, v144
	v_mov_b32_e32 v217, v145
.LBB0_246:
	s_or_b64 exec, exec, s[30:31]
	v_pk_fma_f32 v[108:109], v[74:75], v[108:109], v[78:79]
	v_pk_fma_f32 v[138:139], v[76:77], v[138:139], v[80:81]
	v_pk_fma_f32 v[108:109], v[98:99], v[134:135], v[108:109]
	v_pk_fma_f32 v[140:141], v[86:87], v[140:141], v[90:91]
	v_pk_fma_f32 v[108:109], v[94:95], v[110:111], v[108:109]
	v_pk_fma_f32 v[138:139], v[100:101], v[136:137], v[138:139]
	v_mul_f32_e32 v107, v108, v108
	v_fmamk_f32 v107, v107, 0xbdd2d3e2, v220
	v_mul_f32_e32 v107, v108, v107
	v_exp_f32_e32 v107, v107
	v_pk_fma_f32 v[140:141], v[82:83], v[114:115], v[140:141]
	v_pk_fma_f32 v[138:139], v[96:97], v[112:113], v[138:139]
	v_pk_fma_f32 v[140:141], v[70:71], v[102:103], v[140:141]
	v_add_f32_e32 v107, 1.0, v107
	v_rcp_f32_e32 v107, v107
	v_pk_fma_f32 v[142:143], v[88:89], v[142:143], v[92:93]
	v_mul_f32_e32 v107, v108, v107
	v_mul_f32_e32 v108, v109, v109
	v_fmamk_f32 v108, v108, 0xbdd2d3e2, v220
	v_mul_f32_e32 v108, v109, v108
	v_exp_f32_e32 v108, v108
	v_mul_f32_e32 v107, v107, v140
	v_pk_fma_f32 v[142:143], v[84:85], v[116:117], v[142:143]
	v_add_f32_e32 v108, 1.0, v108
	v_rcp_f32_e32 v108, v108
	v_pk_fma_f32 v[142:143], v[72:73], v[104:105], v[142:143]
	v_mul_f32_e32 v108, v109, v108
	v_mul_f32_e32 v108, v108, v141
	v_mul_f32_e32 v109, v139, v139
	v_cvt_pk_bf16_f32 v108, v107, v108
	v_mul_f32_e32 v107, v138, v138
	v_fmamk_f32 v109, v109, 0xbdd2d3e2, v220
	v_fmamk_f32 v107, v107, 0xbdd2d3e2, v220
	v_mul_f32_e32 v109, v139, v109
	v_mul_f32_e32 v107, v138, v107
	v_exp_f32_e32 v109, v109
	v_exp_f32_e32 v107, v107
	v_add_f32_e32 v109, 1.0, v109
	v_add_f32_e32 v107, 1.0, v107
	v_rcp_f32_e32 v109, v109
	v_rcp_f32_e32 v107, v107
	v_mul_f32_e32 v109, v139, v109
	v_mul_f32_e32 v107, v138, v107
	v_mul_f32_e32 v109, v109, v143
	v_mul_f32_e32 v107, v107, v142
	v_cvt_pk_bf16_f32 v109, v107, v109
	s_and_saveexec_b64 s[30:31], s[4:5]
	s_cbranch_execz .LBB0_248
	v_mov_b32_e32 v107, 0xbd000
	v_lshl_add_u32 v138, v146, 1, v107
	v_mov_b32_e32 v139, v1
	v_lshl_add_u64 v[138:139], s[8:9], 0, v[138:139]
	v_mov_b32_e32 v242, v108
	v_mov_b32_e32 v243, v109
.LBB0_248:
	s_or_b64 exec, exec, s[30:31]
	v_pk_fma_f32 v[134:135], v[74:75], v[134:135], v[78:79]
	v_pk_fma_f32 v[108:109], v[76:77], v[136:137], v[80:81]
	v_pk_fma_f32 v[134:135], v[98:99], v[110:111], v[134:135]
	v_pk_fma_f32 v[76:77], v[76:77], v[112:113], v[80:81]
	v_pk_fma_f32 v[134:135], v[94:95], v[130:131], v[134:135]
	v_pk_fma_f32 v[80:81], v[86:87], v[114:115], v[90:91]
	v_pk_fma_f32 v[86:87], v[86:87], v[102:103], v[90:91]
	v_pk_fma_f32 v[80:81], v[82:83], v[102:103], v[80:81]
	v_pk_fma_f32 v[82:83], v[82:83], v[126:127], v[86:87]
	v_mul_f32_e32 v86, v134, v134
	v_fmamk_f32 v86, v86, 0xbdd2d3e2, v220
	v_mul_f32_e32 v86, v134, v86
	v_exp_f32_e32 v86, v86
	v_pk_fma_f32 v[74:75], v[74:75], v[110:111], v[78:79]
	v_pk_fma_f32 v[78:79], v[88:89], v[116:117], v[92:93]
	v_pk_fma_f32 v[88:89], v[88:89], v[104:105], v[92:93]
	v_mul_f32_e32 v87, v135, v135
	v_pk_fma_f32 v[78:79], v[84:85], v[104:105], v[78:79]
	v_pk_fma_f32 v[84:85], v[84:85], v[128:129], v[88:89]
	v_fmamk_f32 v87, v87, 0xbdd2d3e2, v220
	v_pk_fma_f32 v[78:79], v[72:73], v[128:129], v[78:79]
	v_mul_f32_e32 v87, v135, v87
	v_pk_fma_f32 v[72:73], v[72:73], v[120:121], v[84:85]
	v_add_f32_e32 v84, 1.0, v86
	v_exp_f32_e32 v87, v87
	v_rcp_f32_e32 v84, v84
	v_pk_fma_f32 v[108:109], v[100:101], v[112:113], v[108:109]
	v_pk_fma_f32 v[80:81], v[70:71], v[126:127], v[80:81]
	v_pk_fma_f32 v[108:109], v[96:97], v[132:133], v[108:109]
	v_pk_fma_f32 v[70:71], v[70:71], v[118:119], v[82:83]
	v_mul_f32_e32 v83, v108, v108
	v_add_f32_e32 v85, 1.0, v87
	v_mul_f32_e32 v82, v134, v84
	v_fmamk_f32 v83, v83, 0xbdd2d3e2, v220
	v_mul_f32_e32 v84, v109, v109
	v_rcp_f32_e32 v85, v85
	v_mul_f32_e32 v83, v108, v83
	v_fmamk_f32 v84, v84, 0xbdd2d3e2, v220
	v_exp_f32_e32 v83, v83
	v_mul_f32_e32 v84, v109, v84
	v_exp_f32_e32 v84, v84
	v_mul_f32_e32 v80, v80, v82
	v_mul_f32_e32 v82, v135, v85
	v_mul_f32_e32 v81, v81, v82
	v_add_f32_e32 v82, 1.0, v83
	v_rcp_f32_e32 v82, v82
	v_add_f32_e32 v83, 1.0, v84
	v_rcp_f32_e32 v83, v83
	v_cvt_pk_bf16_f32 v80, v80, v81
	v_mul_f32_e32 v81, v108, v82
	v_pk_fma_f32 v[74:75], v[98:99], v[130:131], v[74:75]
	v_mul_f32_e32 v78, v78, v81
	v_mul_f32_e32 v81, v109, v83
	v_pk_fma_f32 v[74:75], v[94:95], v[122:123], v[74:75]
	v_mul_f32_e32 v79, v79, v81
	v_cvt_pk_bf16_f32 v81, v78, v79
	v_mov_b32_e32 v78, 0xbe800
	v_lshl_add_u32 v102, v146, 1, v78
	v_mul_f32_e32 v78, v74, v74
	v_fmamk_f32 v78, v78, 0xbdd2d3e2, v220
	v_mul_f32_e32 v78, v74, v78
	v_exp_f32_e32 v82, v78
	v_mul_f32_e32 v78, v75, v75
	v_fmamk_f32 v78, v78, 0xbdd2d3e2, v220
	v_mul_f32_e32 v78, v75, v78
	v_exp_f32_e32 v83, v78
	v_add_f32_e32 v82, 1.0, v82
	v_rcp_f32_e32 v82, v82
	v_pk_fma_f32 v[76:77], v[100:101], v[132:133], v[76:77]
	v_add_f32_e32 v83, 1.0, v83
	v_rcp_f32_e32 v83, v83
	v_pk_fma_f32 v[76:77], v[96:97], v[124:125], v[76:77]
	v_mov_b32_e32 v103, v1
	v_mul_f32_e32 v74, v74, v82
	v_lshl_add_u64 v[78:79], s[8:9], 0, v[102:103]
	v_mul_f32_e32 v70, v70, v74
	v_mul_f32_e32 v74, v75, v83
	v_mul_f32_e32 v75, v76, v76
	v_mov_b32_e32 v244, v80
	v_mov_b32_e32 v245, v81
	v_fmamk_f32 v75, v75, 0xbdd2d3e2, v220
	v_mul_f32_e32 v78, v77, v77
	v_mul_f32_e32 v75, v76, v75
	v_fmamk_f32 v78, v78, 0xbdd2d3e2, v220
	v_exp_f32_e32 v75, v75
	v_mul_f32_e32 v78, v77, v78
	v_exp_f32_e32 v78, v78
	v_mul_f32_e32 v71, v71, v74
	v_add_f32_e32 v74, 1.0, v75
	v_rcp_f32_e32 v74, v74
	v_add_f32_e32 v75, 1.0, v78
	v_rcp_f32_e32 v75, v75
	v_cvt_pk_bf16_f32 v70, v70, v71
	v_mul_f32_e32 v71, v76, v74
	v_mul_f32_e32 v71, v72, v71
	v_mul_f32_e32 v72, v77, v75
	v_add_u32_e32 v103, 0x60000, v146
	v_mul_f32_e32 v72, v73, v72
	v_lshlrev_b32_e32 v104, 1, v103
	v_mov_b32_e32 v105, v1
	v_cvt_pk_bf16_f32 v71, v71, v72
	v_lshl_add_u64 v[72:73], s[8:9], 0, v[104:105]
	v_mov_b32_e32 v246, v70
	v_mov_b32_e32 v247, v71
	global_load_dwordx4 v[78:81], v[206:207], off offset:16
	global_load_dwordx4 v[82:85], v[200:201], off offset:16
	global_load_dwordx4 v[74:77], v[202:203], off offset:16
	s_nop 0
	global_load_dwordx4 v[70:73], v[208:209], off offset:16
	global_load_dwordx4 v[94:97], v[214:215], off offset:16
	global_load_dwordx4 v[98:101], v[204:205], off offset:16
	global_load_dwordx4 v[90:93], v[210:211], off offset:16
	global_load_dwordx4 v[86:89], v[212:213], off offset:16
	v_mov_b32_e32 v112, v1
	v_mov_b32_e32 v113, v1
	v_mov_b32_e32 v108, v1
	v_mov_b32_dpp v112, v22 row_shr:1 row_mask:0xf bank_mask:0xf
	v_mov_b32_e32 v109, v1
	v_mov_b32_dpp v113, v23 row_shr:1 row_mask:0xf bank_mask:0xf
	v_mov_b32_dpp v108, v34 row_shr:1 row_mask:0xf bank_mask:0xf
	v_mov_b32_dpp v109, v35 row_shr:1 row_mask:0xf bank_mask:0xf
	v_mov_b32_e32 v114, v1
	v_mov_b32_e32 v115, v1
	v_mov_b32_e32 v110, v1
	v_mov_b32_dpp v114, v24 row_shr:1 row_mask:0xf bank_mask:0xf
	v_mov_b32_e32 v111, v1
	v_mov_b32_dpp v115, v25 row_shr:1 row_mask:0xf bank_mask:0xf
	v_mov_b32_dpp v110, v36 row_shr:1 row_mask:0xf bank_mask:0xf
	v_mov_b32_dpp v111, v37 row_shr:1 row_mask:0xf bank_mask:0xf
	v_mov_b32_e32 v120, v1
	v_mov_b32_e32 v121, v1
	v_mov_b32_e32 v122, v1
	v_mov_b32_dpp v120, v18 row_shr:1 row_mask:0xf bank_mask:0xf
	v_mov_b32_dpp v121, v19 row_shr:1 row_mask:0xf bank_mask:0xf
	v_mov_b32_e32 v123, v1
	v_mov_b32_dpp v122, v20 row_shr:1 row_mask:0xf bank_mask:0xf
	s_waitcnt vmcnt(0) lgkmcnt(0)
	v_pk_fma_f32 v[112:113], v[78:79], v[112:113], v[82:83]
	s_nop 0
	v_pk_fma_f32 v[112:113], v[74:75], v[108:109], v[112:113]
	v_pk_fma_f32 v[114:115], v[80:81], v[114:115], v[84:85]
	v_pk_fma_f32 v[116:117], v[58:59], v[70:71], v[112:113]
	v_pk_fma_f32 v[114:115], v[76:77], v[110:111], v[114:115]
	v_mul_f32_e32 v105, v116, v116
	v_fmamk_f32 v105, v105, 0xbdd2d3e2, v220
	v_mul_f32_e32 v107, v117, v117
	v_mul_f32_e32 v105, v116, v105
	v_fmamk_f32 v107, v107, 0xbdd2d3e2, v220
	v_exp_f32_e32 v105, v105
	v_mul_f32_e32 v107, v117, v107
	v_exp_f32_e32 v107, v107
	v_pk_fma_f32 v[118:119], v[60:61], v[72:73], v[114:115]
	v_add_f32_e32 v105, 1.0, v105
	v_rcp_f32_e32 v105, v105
	v_add_f32_e32 v107, 1.0, v107
	v_rcp_f32_e32 v107, v107
	v_mov_b32_e32 v112, v1
	v_mul_f32_e32 v105, v116, v105
	v_mul_f32_e32 v116, v118, v118
	v_mul_f32_e32 v107, v117, v107
	v_fmamk_f32 v116, v116, 0xbdd2d3e2, v220
	v_mul_f32_e32 v117, v119, v119
	v_mul_f32_e32 v116, v118, v116
	v_fmamk_f32 v117, v117, 0xbdd2d3e2, v220
	v_exp_f32_e32 v116, v116
	v_mul_f32_e32 v117, v119, v117
	v_mov_b32_e32 v113, v1
	v_exp_f32_e32 v117, v117
	v_mov_b32_dpp v112, v30 row_shr:1 row_mask:0xf bank_mask:0xf
	v_mov_b32_dpp v113, v31 row_shr:1 row_mask:0xf bank_mask:0xf
	v_pk_fma_f32 v[120:121], v[98:99], v[120:121], v[94:95]
	v_add_f32_e32 v116, 1.0, v116
	v_pk_fma_f32 v[120:121], v[90:91], v[112:113], v[120:121]
	v_mov_b32_e32 v114, v1
	v_pk_fma_f32 v[120:121], v[54:55], v[86:87], v[120:121]
	v_mov_b32_e32 v115, v1
	v_mul_f32_e32 v105, v105, v120
	v_rcp_f32_e32 v120, v116
	v_add_f32_e32 v116, 1.0, v117
	v_rcp_f32_e32 v117, v116
	v_mov_b32_dpp v123, v21 row_shr:1 row_mask:0xf bank_mask:0xf
	v_mov_b32_dpp v114, v32 row_shr:1 row_mask:0xf bank_mask:0xf
	v_mov_b32_dpp v115, v33 row_shr:1 row_mask:0xf bank_mask:0xf
	v_pk_fma_f32 v[122:123], v[100:101], v[122:123], v[96:97]
	v_mul_f32_e32 v107, v107, v121
	v_pk_fma_f32 v[122:123], v[92:93], v[114:115], v[122:123]
	v_cvt_pk_bf16_f32 v116, v105, v107
	v_mul_f32_e32 v105, v118, v120
	v_pk_fma_f32 v[122:123], v[56:57], v[88:89], v[122:123]
	v_mul_f32_e32 v107, v119, v117
	v_mul_f32_e32 v105, v105, v122
	v_mul_f32_e32 v107, v107, v123
	v_cvt_pk_bf16_f32 v117, v105, v107
	s_and_saveexec_b64 s[30:31], s[4:5]
	s_cbranch_execz .LBB0_250
	v_mad_u64_u32 v[118:119], s[34:35], v237, s23, v[192:193]
	v_lshl_or_b32 v118, v118, 1, 8
	v_mov_b32_e32 v119, v1
	v_lshl_add_u64 v[118:119], s[8:9], 0, v[118:119]
	v_mov_b32_e32 v124, v178
	v_mov_b32_e32 v125, v179
	v_mov_b32_e32 v126, v116
	v_mov_b32_e32 v127, v117
	global_store_dwordx4 v[118:119], v[124:127], off offset:-8
.LBB0_250:
	s_or_b64 exec, exec, s[30:31]
	v_pk_fma_f32 v[108:109], v[78:79], v[108:109], v[82:83]
	v_pk_fma_f32 v[112:113], v[98:99], v[112:113], v[94:95]
	v_pk_fma_f32 v[108:109], v[58:59], v[74:75], v[108:109]
	v_pk_fma_f32 v[110:111], v[80:81], v[110:111], v[84:85]
	v_pk_fma_f32 v[108:109], v[66:67], v[70:71], v[108:109]
	v_pk_fma_f32 v[112:113], v[54:55], v[90:91], v[112:113]
	v_mul_f32_e32 v105, v108, v108
	v_mul_f32_e32 v107, v109, v109
	v_fmamk_f32 v105, v105, 0xbdd2d3e2, v220
	v_fmamk_f32 v107, v107, 0xbdd2d3e2, v220
	v_mul_f32_e32 v105, v108, v105
	v_mul_f32_e32 v107, v109, v107
	v_exp_f32_e32 v105, v105
	v_exp_f32_e32 v107, v107
	v_pk_fma_f32 v[110:111], v[60:61], v[76:77], v[110:111]
	v_pk_fma_f32 v[112:113], v[62:63], v[86:87], v[112:113]
	v_add_f32_e32 v105, 1.0, v105
	v_add_f32_e32 v107, 1.0, v107
	v_rcp_f32_e32 v105, v105
	v_rcp_f32_e32 v107, v107
	v_pk_fma_f32 v[110:111], v[68:69], v[72:73], v[110:111]
	v_pk_fma_f32 v[114:115], v[100:101], v[114:115], v[96:97]
	v_mul_f32_e32 v105, v108, v105
	v_mul_f32_e32 v107, v109, v107
	v_mul_f32_e32 v105, v105, v112
	v_mul_f32_e32 v107, v107, v113
	v_cvt_pk_bf16_f32 v108, v105, v107
	v_mul_f32_e32 v105, v110, v110
	v_mul_f32_e32 v107, v111, v111
	v_fmamk_f32 v105, v105, 0xbdd2d3e2, v220
	v_fmamk_f32 v107, v107, 0xbdd2d3e2, v220
	v_mul_f32_e32 v105, v110, v105
	v_mul_f32_e32 v107, v111, v107
	v_exp_f32_e32 v105, v105
	v_exp_f32_e32 v107, v107
	v_pk_fma_f32 v[114:115], v[56:57], v[92:93], v[114:115]
	v_add_f32_e32 v105, 1.0, v105
	v_add_f32_e32 v107, 1.0, v107
	v_rcp_f32_e32 v105, v105
	v_rcp_f32_e32 v107, v107
	v_pk_fma_f32 v[114:115], v[64:65], v[88:89], v[114:115]
	v_mul_f32_e32 v105, v110, v105
	v_mul_f32_e32 v107, v111, v107
	v_mul_f32_e32 v105, v105, v114
	v_mul_f32_e32 v107, v107, v115
	v_cvt_pk_bf16_f32 v109, v105, v107
	s_and_saveexec_b64 s[30:31], s[4:5]
	s_cbranch_execz .LBB0_252
	v_mov_b32_e32 v105, 0xfff3d008
	v_lshl_add_u32 v110, v103, 1, v105
	v_mov_b32_e32 v111, v1
	v_lshl_add_u64 v[110:111], s[8:9], 0, v[110:111]
	v_mov_b32_e32 v128, v180
	v_mov_b32_e32 v129, v181
	v_mov_b32_e32 v130, v108
	v_mov_b32_e32 v131, v109
	global_store_dwordx4 v[110:111], v[128:131], off offset:-8
.LBB0_252:
	s_or_b64 exec, exec, s[30:31]
	v_pk_fma_f32 v[58:59], v[58:59], v[78:79], v[82:83]
	v_pk_fma_f32 v[60:61], v[60:61], v[80:81], v[84:85]
	v_pk_fma_f32 v[58:59], v[66:67], v[74:75], v[58:59]
	v_pk_fma_f32 v[66:67], v[66:67], v[78:79], v[82:83]
	v_pk_fma_f32 v[60:61], v[68:69], v[76:77], v[60:61]
	v_pk_fma_f32 v[58:59], v[22:23], v[70:71], v[58:59]
	v_pk_fma_f32 v[68:69], v[68:69], v[80:81], v[84:85]
	v_pk_fma_f32 v[22:23], v[22:23], v[74:75], v[66:67]
	v_pk_fma_f32 v[60:61], v[24:25], v[72:73], v[60:61]
	v_pk_fma_f32 v[24:25], v[24:25], v[76:77], v[68:69]
	v_pk_fma_f32 v[22:23], v[34:35], v[70:71], v[22:23]
	v_pk_fma_f32 v[34:35], v[56:57], v[100:101], v[96:97]
	v_pk_fma_f32 v[24:25], v[36:37], v[72:73], v[24:25]
	v_pk_fma_f32 v[36:37], v[54:55], v[98:99], v[94:95]
	v_pk_fma_f32 v[34:35], v[64:65], v[92:93], v[34:35]
	v_pk_fma_f32 v[54:55], v[64:65], v[100:101], v[96:97]
	v_pk_fma_f32 v[34:35], v[20:21], v[88:89], v[34:35]
	v_pk_fma_f32 v[20:21], v[20:21], v[92:93], v[54:55]
	v_mul_f32_e32 v54, v58, v58
	v_mul_f32_e32 v55, v59, v59
	v_fmamk_f32 v54, v54, 0xbdd2d3e2, v220
	v_fmamk_f32 v55, v55, 0xbdd2d3e2, v220
	v_mul_f32_e32 v54, v58, v54
	v_mul_f32_e32 v55, v59, v55
	v_exp_f32_e32 v54, v54
	v_exp_f32_e32 v55, v55
	v_pk_fma_f32 v[20:21], v[32:33], v[88:89], v[20:21]
	v_pk_fma_f32 v[36:37], v[62:63], v[90:91], v[36:37]
	v_add_f32_e32 v32, 1.0, v54
	v_add_f32_e32 v33, 1.0, v55
	v_rcp_f32_e32 v32, v32
	v_rcp_f32_e32 v33, v33
	v_pk_fma_f32 v[56:57], v[62:63], v[98:99], v[94:95]
	v_pk_fma_f32 v[36:37], v[18:19], v[86:87], v[36:37]
	v_pk_fma_f32 v[18:19], v[18:19], v[90:91], v[56:57]
	v_or_b32_e32 v0, 8, v0
	v_pk_fma_f32 v[18:19], v[30:31], v[86:87], v[18:19]
	v_mul_f32_e32 v30, v58, v32
	v_mul_f32_e32 v31, v59, v33
	v_mul_f32_e32 v32, v60, v60
	v_mul_f32_e32 v33, v61, v61
	v_fmamk_f32 v32, v32, 0xbdd2d3e2, v220
	v_fmamk_f32 v33, v33, 0xbdd2d3e2, v220
	v_mul_f32_e32 v32, v60, v32
	v_mul_f32_e32 v33, v61, v33
	v_exp_f32_e32 v32, v32
	v_exp_f32_e32 v33, v33
	v_mul_f32_e32 v30, v36, v30
	v_mul_f32_e32 v31, v37, v31
	v_add_f32_e32 v32, 1.0, v32
	v_add_f32_e32 v33, 1.0, v33
	v_rcp_f32_e32 v32, v32
	v_rcp_f32_e32 v33, v33
	v_cvt_pk_bf16_f32 v30, v30, v31
	v_mov_b32_e32 v36, v1
	v_mul_f32_e32 v31, v60, v32
	v_mul_f32_e32 v32, v61, v33
	v_mul_f32_e32 v31, v34, v31
	v_mul_f32_e32 v32, v35, v32
	v_cvt_pk_bf16_f32 v31, v31, v32
	v_mul_f32_e32 v32, v22, v22
	v_fmamk_f32 v32, v32, 0xbdd2d3e2, v220
	v_mul_f32_e32 v32, v22, v32
	v_exp_f32_e32 v34, v32
	v_mul_f32_e32 v32, v23, v23
	v_fmamk_f32 v32, v32, 0xbdd2d3e2, v220
	v_mul_f32_e32 v32, v23, v32
	v_exp_f32_e32 v35, v32
	v_lshl_add_u64 v[32:33], s[8:9], 0, v[0:1]
	v_add_f32_e32 v0, 1.0, v34
	v_rcp_f32_e32 v0, v0
	v_add_f32_e32 v34, 1.0, v35
	v_rcp_f32_e32 v34, v34
	v_mov_b32_e32 v132, v194
	v_mov_b32_e32 v133, v195
	v_mov_b32_e32 v134, v30
	v_mov_b32_e32 v135, v31
	global_store_dwordx4 v[32:33], v[132:135], off offset:-8
	v_mul_f32_e32 v0, v22, v0
	v_mul_f32_e32 v0, v18, v0
	v_mul_f32_e32 v18, v23, v34
	v_mul_f32_e32 v22, v24, v24
	v_mul_f32_e32 v23, v25, v25
	v_fmamk_f32 v22, v22, 0xbdd2d3e2, v220
	v_fmamk_f32 v23, v23, 0xbdd2d3e2, v220
	v_mul_f32_e32 v22, v24, v22
	v_mul_f32_e32 v23, v25, v23
	v_exp_f32_e32 v22, v22
	v_exp_f32_e32 v23, v23
	v_mul_f32_e32 v18, v19, v18
	v_cvt_pk_bf16_f32 v18, v0, v18
	v_add_f32_e32 v19, 1.0, v22
	v_add_f32_e32 v22, 1.0, v23
	v_rcp_f32_e32 v19, v19
	v_rcp_f32_e32 v22, v22
	v_mov_b32_e32 v23, v1
	v_mov_b32_e32 v34, v1
	v_mul_f32_e32 v0, v24, v19
	v_mul_f32_e32 v19, v25, v22
	v_mul_f32_e32 v0, v20, v0
	v_mul_f32_e32 v19, v21, v19
	v_cvt_pk_bf16_f32 v19, v0, v19
	v_or_b32_e32 v0, 8, v106
	v_lshl_add_u64 v[20:21], s[8:9], 0, v[0:1]
	v_mov_b32_e32 v22, v1
	v_mov_b32_e32 v136, v196
	v_mov_b32_e32 v137, v197
	v_mov_b32_e32 v138, v18
	v_mov_b32_e32 v139, v19
	global_store_dwordx4 v[20:21], v[136:139], off offset:-8
	v_mov_b32_e32 v18, v1
	v_mov_b32_dpp v22, v6 row_shr:1 row_mask:0xf bank_mask:0xf
	v_mov_b32_e32 v19, v1
	v_mov_b32_dpp v23, v7 row_shr:1 row_mask:0xf bank_mask:0xf
	v_mov_b32_dpp v18, v14 row_shr:1 row_mask:0xf bank_mask:0xf
	v_mov_b32_dpp v19, v15 row_shr:1 row_mask:0xf bank_mask:0xf
	v_pk_fma_f32 v[22:23], v[78:79], v[22:23], v[82:83]
	v_mov_b32_e32 v24, v1
	v_pk_fma_f32 v[22:23], v[74:75], v[18:19], v[22:23]
	v_mov_b32_e32 v25, v1
	v_pk_fma_f32 v[30:31], v[38:39], v[70:71], v[22:23]
	v_mov_b32_e32 v35, v1
	v_mul_f32_e32 v0, v30, v30
	v_fmamk_f32 v0, v0, 0xbdd2d3e2, v220
	v_mul_f32_e32 v54, v31, v31
	v_mul_f32_e32 v0, v30, v0
	v_fmamk_f32 v54, v54, 0xbdd2d3e2, v220
	v_exp_f32_e32 v0, v0
	v_mul_f32_e32 v54, v31, v54
	v_exp_f32_e32 v54, v54
	v_mov_b32_e32 v20, v1
	v_add_f32_e32 v0, 1.0, v0
	v_rcp_f32_e32 v0, v0
	v_add_f32_e32 v54, 1.0, v54
	v_mov_b32_dpp v24, v8 row_shr:1 row_mask:0xf bank_mask:0xf
	v_mov_b32_e32 v21, v1
	v_mov_b32_dpp v25, v9 row_shr:1 row_mask:0xf bank_mask:0xf
	v_mov_b32_e32 v22, v1
	v_mov_b32_dpp v34, v10 row_shr:1 row_mask:0xf bank_mask:0xf
	v_mov_b32_e32 v23, v1
	v_mov_b32_dpp v35, v11 row_shr:1 row_mask:0xf bank_mask:0xf
	v_rcp_f32_e32 v54, v54
	v_mov_b32_dpp v20, v16 row_shr:1 row_mask:0xf bank_mask:0xf
	v_mov_b32_dpp v21, v17 row_shr:1 row_mask:0xf bank_mask:0xf
	v_pk_fma_f32 v[24:25], v[80:81], v[24:25], v[84:85]
	v_mov_b32_dpp v22, v26 row_shr:1 row_mask:0xf bank_mask:0xf
	v_mov_b32_dpp v23, v27 row_shr:1 row_mask:0xf bank_mask:0xf
	v_pk_fma_f32 v[34:35], v[98:99], v[34:35], v[94:95]
	v_pk_fma_f32 v[24:25], v[76:77], v[20:21], v[24:25]
	v_pk_fma_f32 v[34:35], v[90:91], v[22:23], v[34:35]
	v_pk_fma_f32 v[32:33], v[40:41], v[72:73], v[24:25]
	v_pk_fma_f32 v[34:35], v[46:47], v[86:87], v[34:35]
	v_mul_f32_e32 v0, v30, v0
	v_mul_f32_e32 v0, v0, v34
	v_mul_f32_e32 v30, v31, v54
	v_mul_f32_e32 v31, v32, v32
	v_mul_f32_e32 v34, v33, v33
	v_fmamk_f32 v31, v31, 0xbdd2d3e2, v220
	v_fmamk_f32 v34, v34, 0xbdd2d3e2, v220
	v_mul_f32_e32 v31, v32, v31
	v_mul_f32_e32 v34, v33, v34
	v_exp_f32_e32 v31, v31
	v_exp_f32_e32 v34, v34
	v_mov_b32_e32 v37, v1
	v_mov_b32_e32 v24, v1
	v_add_f32_e32 v31, 1.0, v31
	v_add_f32_e32 v34, 1.0, v34
	v_rcp_f32_e32 v31, v31
	v_rcp_f32_e32 v34, v34
	v_mov_b32_dpp v36, v12 row_shr:1 row_mask:0xf bank_mask:0xf
	v_mov_b32_e32 v25, v1
	v_mov_b32_dpp v37, v13 row_shr:1 row_mask:0xf bank_mask:0xf
	v_mov_b32_dpp v24, v28 row_shr:1 row_mask:0xf bank_mask:0xf
	v_mov_b32_dpp v25, v29 row_shr:1 row_mask:0xf bank_mask:0xf
	v_pk_fma_f32 v[36:37], v[100:101], v[36:37], v[96:97]
	v_mul_f32_e32 v30, v30, v35
	v_pk_fma_f32 v[36:37], v[92:93], v[24:25], v[36:37]
	v_cvt_pk_bf16_f32 v30, v0, v30
	v_mul_f32_e32 v0, v32, v31
	v_pk_fma_f32 v[36:37], v[48:49], v[88:89], v[36:37]
	v_mul_f32_e32 v31, v33, v34
	v_mul_f32_e32 v31, v31, v37
	v_mul_f32_e32 v0, v0, v36
	v_cvt_pk_bf16_f32 v31, v0, v31
	s_and_saveexec_b64 s[30:31], s[4:5]
	s_cbranch_execz .LBB0_254
	v_mov_b32_e32 v0, 0xffffb808
	v_lshl_add_u32 v0, v103, 1, v0
	v_lshl_add_u64 v[32:33], s[8:9], 0, v[0:1]
	v_mov_b32_e32 v140, v216
	v_mov_b32_e32 v141, v217
	v_mov_b32_e32 v142, v30
	v_mov_b32_e32 v143, v31
	global_store_dwordx4 v[32:33], v[140:143], off offset:-8
.LBB0_254:
	s_or_b64 exec, exec, s[30:31]
	v_pk_fma_f32 v[18:19], v[78:79], v[18:19], v[82:83]
	v_pk_fma_f32 v[20:21], v[80:81], v[20:21], v[84:85]
	v_pk_fma_f32 v[18:19], v[38:39], v[74:75], v[18:19]
	v_pk_fma_f32 v[22:23], v[98:99], v[22:23], v[94:95]
	v_pk_fma_f32 v[18:19], v[42:43], v[70:71], v[18:19]
	v_pk_fma_f32 v[20:21], v[40:41], v[76:77], v[20:21]
	v_mul_f32_e32 v0, v18, v18
	v_fmamk_f32 v0, v0, 0xbdd2d3e2, v220
	v_mul_f32_e32 v0, v18, v0
	v_exp_f32_e32 v0, v0
	v_pk_fma_f32 v[22:23], v[46:47], v[90:91], v[22:23]
	v_pk_fma_f32 v[20:21], v[44:45], v[72:73], v[20:21]
	v_pk_fma_f32 v[22:23], v[50:51], v[86:87], v[22:23]
	v_add_f32_e32 v0, 1.0, v0
	v_rcp_f32_e32 v0, v0
	v_pk_fma_f32 v[24:25], v[100:101], v[24:25], v[96:97]
	v_mul_f32_e32 v0, v18, v0
	v_mul_f32_e32 v18, v19, v19
	v_fmamk_f32 v18, v18, 0xbdd2d3e2, v220
	v_mul_f32_e32 v18, v19, v18
	v_exp_f32_e32 v18, v18
	v_mul_f32_e32 v0, v0, v22
	v_pk_fma_f32 v[24:25], v[48:49], v[92:93], v[24:25]
	v_add_f32_e32 v18, 1.0, v18
	v_rcp_f32_e32 v18, v18
	v_pk_fma_f32 v[24:25], v[52:53], v[88:89], v[24:25]
	v_mul_f32_e32 v18, v19, v18
	v_mul_f32_e32 v18, v18, v23
	v_mul_f32_e32 v19, v21, v21
	v_cvt_pk_bf16_f32 v18, v0, v18
	v_mul_f32_e32 v0, v20, v20
	v_fmamk_f32 v19, v19, 0xbdd2d3e2, v220
	v_fmamk_f32 v0, v0, 0xbdd2d3e2, v220
	v_mul_f32_e32 v19, v21, v19
	v_mul_f32_e32 v0, v20, v0
	v_exp_f32_e32 v19, v19
	v_exp_f32_e32 v0, v0
	v_add_f32_e32 v19, 1.0, v19
	v_add_f32_e32 v0, 1.0, v0
	v_rcp_f32_e32 v19, v19
	v_rcp_f32_e32 v0, v0
	v_mul_f32_e32 v19, v21, v19
	v_mul_f32_e32 v0, v20, v0
	v_mul_f32_e32 v19, v19, v25
	v_mul_f32_e32 v0, v0, v24
	v_cvt_pk_bf16_f32 v19, v0, v19
	s_and_saveexec_b64 s[30:31], s[4:5]
	s_cbranch_execz .LBB0_256
	v_mov_b32_e32 v0, 0xffffd008
	v_lshl_add_u32 v0, v103, 1, v0
	v_lshl_add_u64 v[20:21], s[8:9], 0, v[0:1]
	v_mov_b32_e32 v144, v242
	v_mov_b32_e32 v145, v243
	v_mov_b32_e32 v146, v18
	v_mov_b32_e32 v147, v19
	global_store_dwordx4 v[20:21], v[144:147], off offset:-8
.LBB0_256:
	s_or_b64 exec, exec, s[30:31]
	v_pk_fma_f32 v[24:25], v[46:47], v[98:99], v[94:95]
	v_pk_fma_f32 v[20:21], v[50:51], v[98:99], v[94:95]
	v_pk_fma_f32 v[24:25], v[50:51], v[90:91], v[24:25]
	v_pk_fma_f32 v[20:21], v[10:11], v[90:91], v[20:21]
	v_pk_fma_f32 v[10:11], v[10:11], v[86:87], v[24:25]
	v_pk_fma_f32 v[24:25], v[42:43], v[78:79], v[82:83]
	v_pk_fma_f32 v[22:23], v[48:49], v[100:101], v[96:97]
	v_pk_fma_f32 v[24:25], v[6:7], v[74:75], v[24:25]
	v_pk_fma_f32 v[18:19], v[52:53], v[100:101], v[96:97]
	v_pk_fma_f32 v[14:15], v[14:15], v[70:71], v[24:25]
	v_pk_fma_f32 v[24:25], v[38:39], v[78:79], v[82:83]
	v_pk_fma_f32 v[22:23], v[52:53], v[92:93], v[22:23]
	v_pk_fma_f32 v[24:25], v[42:43], v[74:75], v[24:25]
	v_pk_fma_f32 v[18:19], v[12:13], v[92:93], v[18:19]
	v_pk_fma_f32 v[6:7], v[6:7], v[70:71], v[24:25]
	v_pk_fma_f32 v[12:13], v[12:13], v[88:89], v[22:23]
	v_mul_f32_e32 v0, v6, v6
	v_mul_f32_e32 v24, v7, v7
	v_fmamk_f32 v0, v0, 0xbdd2d3e2, v220
	v_fmamk_f32 v24, v24, 0xbdd2d3e2, v220
	v_mul_f32_e32 v0, v6, v0
	v_mul_f32_e32 v24, v7, v24
	v_exp_f32_e32 v0, v0
	v_exp_f32_e32 v24, v24
	v_pk_fma_f32 v[22:23], v[44:45], v[80:81], v[84:85]
	v_pk_fma_f32 v[20:21], v[26:27], v[86:87], v[20:21]
	v_add_f32_e32 v0, 1.0, v0
	v_add_f32_e32 v24, 1.0, v24
	v_pk_fma_f32 v[22:23], v[8:9], v[76:77], v[22:23]
	v_rcp_f32_e32 v0, v0
	v_rcp_f32_e32 v24, v24
	v_pk_fma_f32 v[16:17], v[16:17], v[72:73], v[22:23]
	v_pk_fma_f32 v[22:23], v[40:41], v[80:81], v[84:85]
	v_mul_f32_e32 v0, v6, v0
	v_pk_fma_f32 v[22:23], v[44:45], v[76:77], v[22:23]
	v_mul_f32_e32 v6, v7, v24
	v_pk_fma_f32 v[8:9], v[8:9], v[72:73], v[22:23]
	v_mul_f32_e32 v0, v10, v0
	v_mul_f32_e32 v7, v8, v8
	v_fmamk_f32 v7, v7, 0xbdd2d3e2, v220
	v_mul_f32_e32 v7, v8, v7
	v_exp_f32_e32 v7, v7
	v_mul_f32_e32 v10, v9, v9
	v_fmamk_f32 v10, v10, 0xbdd2d3e2, v220
	v_mul_f32_e32 v10, v9, v10
	v_exp_f32_e32 v10, v10
	v_add_f32_e32 v7, 1.0, v7
	v_rcp_f32_e32 v7, v7
	v_mul_f32_e32 v6, v11, v6
	v_add_f32_e32 v10, 1.0, v10
	v_rcp_f32_e32 v10, v10
	v_cvt_pk_bf16_f32 v6, v0, v6
	v_mul_f32_e32 v0, v8, v7
	v_mul_f32_e32 v8, v14, v14
	v_fmamk_f32 v8, v8, 0xbdd2d3e2, v220
	v_mul_f32_e32 v8, v14, v8
	v_mul_f32_e32 v7, v9, v10
	v_exp_f32_e32 v10, v8
	v_mul_f32_e32 v8, v15, v15
	v_mul_f32_e32 v0, v12, v0
	v_mul_f32_e32 v7, v13, v7
	v_fmamk_f32 v8, v8, 0xbdd2d3e2, v220
	v_cvt_pk_bf16_f32 v7, v0, v7
	v_or_b32_e32 v0, 8, v102
	v_mul_f32_e32 v8, v15, v8
	v_exp_f32_e32 v11, v8
	v_lshl_add_u64 v[8:9], s[8:9], 0, v[0:1]
	v_mov_b32_e32 v148, v244
	v_mov_b32_e32 v149, v245
	v_mov_b32_e32 v150, v6
	v_mov_b32_e32 v151, v7
	global_store_dwordx4 v[8:9], v[148:151], off offset:-8
	v_mul_f32_e32 v7, v16, v16
	v_mul_f32_e32 v8, v17, v17
	v_fmamk_f32 v7, v7, 0xbdd2d3e2, v220
	v_fmamk_f32 v8, v8, 0xbdd2d3e2, v220
	v_mul_f32_e32 v7, v16, v7
	v_mul_f32_e32 v8, v17, v8
	v_exp_f32_e32 v7, v7
	v_exp_f32_e32 v8, v8
	v_add_f32_e32 v0, 1.0, v10
	v_add_f32_e32 v10, 1.0, v11
	v_rcp_f32_e32 v0, v0
	v_rcp_f32_e32 v10, v10
	v_add_f32_e32 v7, 1.0, v7
	v_add_f32_e32 v8, 1.0, v8
	v_rcp_f32_e32 v7, v7
	v_rcp_f32_e32 v8, v8
	v_mul_f32_e32 v0, v14, v0
	v_mul_f32_e32 v6, v15, v10
	v_mul_f32_e32 v0, v20, v0
	v_mul_f32_e32 v6, v21, v6
	v_pk_fma_f32 v[18:19], v[28:29], v[88:89], v[18:19]
	v_cvt_pk_bf16_f32 v6, v0, v6
	v_mul_f32_e32 v0, v16, v7
	v_mul_f32_e32 v7, v17, v8
	v_mul_f32_e32 v0, v18, v0
	v_mul_f32_e32 v7, v19, v7
	v_cvt_pk_bf16_f32 v7, v0, v7
	v_or_b32_e32 v0, 8, v104
	v_lshl_add_u64 v[8:9], s[8:9], 0, v[0:1]
	s_andn2_b64 vcc, exec, s[6:7]
	s_mov_b64 s[6:7], -1
	v_mov_b32_e32 v152, v246
	v_mov_b32_e32 v153, v247
	v_mov_b32_e32 v154, v6
	v_mov_b32_e32 v155, v7
	global_store_dwordx4 v[8:9], v[152:155], off offset:-8
	s_cbranch_vccnz .LBB0_209
	s_andn2_b64 vcc, exec, s[2:3]
	s_cbranch_vccnz .LBB0_208
	s_barrier
	s_branch .LBB0_208
